# peel + attention stagger: waves 4-7 s_sleep 10 before QK^T each block step
# baseline (speedup 1.0000x reference)
; #define LAS __attribute__((address_space(3)))
; __device__ __forceinline__ unsigned swz(unsigned row) { return ((row & 3u) << 2) | ((row >> 2) & 3u); }
; __device__ __forceinline__ void segment(LAS unsigned char* lds, const bf16* __restrict__ QKV, bf16* __restrict__ Og, float* __restrict__ L2, int bl, int g, int h, int r, int dil, int n0, int cnt, int tid) {
;     const int lane = tid & 63, w = __builtin_amdgcn_readfirstlane(tid >> 6), lq = lane & 15, gq = lane >> 4;
;     const size_t rowbase = (size_t)bl * SEQ + r;
;     const bf16* qcol = QKV + (size_t)g * 3072 + h * 128;
;     const int srow = tid >> 4, sch = tid & 15;
;     const unsigned sdst = 256u * srow + 16u * ((unsigned)sch ^ swz(srow));
;     const unsigned sdstv = VBASE + 256u * srow + 16u * ((unsigned)sch ^ (2u * (srow & 7)));
;     unsigned koff[4], voff[8];
; #pragma unroll
;     for (int s = 0; s < 4; ++s) koff[s] = 256u * lq + 16u * ((unsigned)(4 * s + gq) ^ swz(lq));
;     { const unsigned q4 = lq >> 2, p4 = lq & 3, rowv = 4 * gq + q4;
; #pragma unroll
;       for (int c = 0; c < 8; ++c) voff[c] = 256u * rowv + 16u * ((unsigned)(2 * c + (p4 & 1)) ^ (2u * (rowv & 7))) + 8u * (p4 >> 1); }
;     const float cb = exp2f(-8.0f * (float)(g * 8 + h + 1) / 24.0f) * (float)dil * 1.4426950408889634f;
;     const float basel = -cb * (float)(128 + lq - 4 * gq);
;     v4u kv[8]; bf16x8 qn[4], qf[4];
; __device__ __forceinline__ void phase(LAS unsigned char* lds, const bf16* QKV, bf16* Og, float* L2, int tid) {
;     for (int it = blockIdx.x; it < 768; it += gridDim.x) {
.LBB0_276:
	s_cmp_lt_i32 s84, 3
	s_cselect_b64 s[4:5], -1, 0
	s_add_u32 s2, s82, 0x200000
	s_addc_u32 s3, s83, 0
	v_writelane_b32 v239, s2, 51
	s_and_b64 s[0:1], s[4:5], s[0:1]
	s_andn2_b64 vcc, exec, s[0:1]
	v_writelane_b32 v239, s3, 52
	v_writelane_b32 v239, s80, 53
	s_nop 1
	v_writelane_b32 v239, s81, 54
	v_writelane_b32 v239, s82, 55
	v_writelane_b32 v239, s83, 56
	v_writelane_b32 v239, s84, 57
	v_writelane_b32 v239, s85, 58
	v_writelane_b32 v239, s86, 59
	v_writelane_b32 v239, s87, 60
	s_cbranch_vccnz .LBB0_302
	v_readfirstlane_b32 s99, v154
	s_nop 3
	s_lshr_b32 s99, s99, 6
	s_cmp_ge_u32 s99, 4
	s_cselect_b32 s99, 1, 0
	v_writelane_b32 v239, s4, 61
	s_nop 1
	v_writelane_b32 v239, s5, 62
	s_nop 0
	v_readlane_b32 s0, v239, 0
	s_cmpk_gt_i32 s0, 0x2ff
	s_cbranch_scc1 .LBB0_301
	v_lshlrev_b32_e32 v5, 2, v154
	v_and_b32_e32 v119, 15, v154
	v_bfe_u32 v1, v154, 4, 2
	v_and_b32_e32 v6, 12, v5
	v_bfe_u32 v7, v154, 2, 2
	v_lshrrev_b32_e32 v2, 2, v154
	v_lshlrev_b32_e32 v4, 8, v119
	v_or_b32_e32 v8, v6, v7
	v_bitop3_b32 v6, v6, v1, v7 bitop3:0x36
	v_lshrrev_b32_e32 v122, 4, v154
	v_and_b32_e32 v2, 12, v2
	v_bfe_u32 v3, v154, 6, 2
	v_lshl_or_b32 v123, v6, 4, v4
	v_bitop3_b32 v6, v1, v8, 4 bitop3:0x36
	v_lshlrev_b32_e32 v0, 8, v122
	v_bitop3_b32 v2, v2, v119, v3 bitop3:0x36
	v_lshl_or_b32 v124, v6, 4, v4
	v_bitop3_b32 v6, v1, v8, 8 bitop3:0x36
	v_lshl_or_b32 v125, v6, 4, v4
	v_bitop3_b32 v6, v1, v8, 12 bitop3:0x36
	v_lshl_or_b32 v127, v2, 4, v0
	v_lshlrev_b32_e32 v2, 2, v1
	v_lshl_or_b32 v126, v6, 4, v4
	v_or_b32_e32 v4, v2, v7
	v_lshlrev_b32_e32 v7, 1, v4
	v_and_b32_e32 v6, 1, v154
	v_and_b32_e32 v8, 14, v7
	v_and_b32_e32 v5, 8, v5
	v_lshl_or_b32 v4, v4, 8, v5
	v_or_b32_e32 v5, v8, v6
	v_lshl_or_b32 v128, v5, 4, v4
	v_or_b32_e32 v5, 2, v6
	v_bitop3_b32 v5, v7, v5, 14 bitop3:0x6c
	v_lshl_or_b32 v129, v5, 4, v4
	v_or_b32_e32 v5, 4, v6
	v_bitop3_b32 v5, v7, v5, 14 bitop3:0x6c
	v_lshrrev_b32_e32 v3, 3, v154
	v_lshl_or_b32 v130, v5, 4, v4
	v_or_b32_e32 v5, 6, v6
	v_bitop3_b32 v3, v3, v119, 14 bitop3:0x6c
	v_bitop3_b32 v5, v7, v5, 14 bitop3:0x6c
	v_lshlrev_b32_e32 v3, 4, v3
	v_lshl_or_b32 v131, v5, 4, v4
	v_or_b32_e32 v5, 8, v6
	s_mov_b32 s0, 0x10000
	v_bitop3_b32 v5, v7, v5, 14 bitop3:0x6c
	v_or3_b32 v136, v3, v0, s0
	v_or_b32_e32 v0, 0x80, v119
	v_lshl_or_b32 v132, v5, 4, v4
	v_or_b32_e32 v5, 10, v6
	v_sub_u32_e32 v0, v0, v2
	v_bitop3_b32 v5, v7, v5, 14 bitop3:0x6c
	v_cvt_f32_ubyte0_e32 v137, v0
	v_or_b32_e32 v0, 1, v2
	v_lshl_or_b32 v133, v5, 4, v4
	v_or_b32_e32 v5, 12, v6
	v_cmp_ge_u32_e64 s[4:5], v2, v119
	v_cmp_ge_u32_e64 s[6:7], v0, v119
	v_or_b32_e32 v0, 2, v2
	v_or_b32_e32 v3, 3, v2
	v_cmp_gt_u32_e64 s[12:13], v2, v119
	v_cmp_lt_u32_e64 s[14:15], v2, v119
	v_mbcnt_lo_u32_b32 v2, -1, 0
	v_bitop3_b32 v5, v7, v5, 14 bitop3:0x6c
	v_mbcnt_hi_u32_b32 v2, -1, v2
	v_lshl_or_b32 v134, v5, 4, v4
	v_bitop3_b32 v5, v7, v6, 14 bitop3:0x4e
	v_and_b32_e32 v6, 64, v2
	v_lshl_or_b32 v135, v5, 4, v4
	v_xor_b32_e32 v5, 16, v2
	v_add_u32_e32 v6, 64, v6
	v_cmp_lt_i32_e32 vcc, v5, v6
	v_cmp_ge_u32_e64 s[10:11], v3, v119
	v_cmp_gt_u32_e64 s[18:19], v3, v119
	v_cndmask_b32_e32 v5, v2, v5, vcc
	v_lshlrev_b32_e32 v139, 2, v5
	v_xor_b32_e32 v5, 32, v2
	v_cmp_lt_i32_e32 vcc, v5, v6
	v_mov_b32_e32 v3, 0
	s_mov_b64 s[0:1], 0x7c00000
	v_cndmask_b32_e32 v2, v2, v5, vcc
	v_lshlrev_b32_e32 v140, 2, v2
	v_lshlrev_b32_e32 v2, 4, v1
	v_lshl_add_u64 v[6:7], s[82:83], 0, v[2:3]
	v_cmp_ge_u32_e64 s[8:9], v0, v119
	v_cmp_gt_u32_e64 s[16:17], v0, v119
	v_lshlrev_b32_e32 v0, 3, v119
	v_lshlrev_b32_e32 v4, 3, v1
	v_lshl_add_u64 v[68:69], s[80:81], 0, v[2:3]
	v_lshl_add_u64 v[70:71], v[6:7], 0, s[0:1]
	v_lshlrev_b32_e32 v2, 4, v119
	v_readlane_b32 s0, v239, 0
	v_or_b32_e32 v138, 0xffffff80, v122
	s_mov_b32 s41, 0
	v_cmp_eq_u32_e64 s[2:3], 0, v1
	v_lshl_add_u64 v[72:73], s[82:83], 0, v[2:3]
	v_mov_b32_e32 v141, 0x42800000
	v_lshlrev_b32_e32 v74, 1, v4
	v_mov_b32_e32 v75, v3
	v_lshlrev_b32_e32 v76, 1, v0
	v_mov_b32_e32 v77, v3
	v_mov_b64_e32 v[78:79], 0x2d0000
	v_mov_b64_e32 v[80:81], 0x240000
	v_mov_b64_e32 v[82:83], 0x360000
	v_mov_b64_e32 v[84:85], 0x3f0000
	v_mov_b32_e32 v142, 0xff800000
	s_mov_b32 s25, s0
	v_writelane_b32 v239, s64, 63
	s_nop 1
	v_writelane_b32 v238, s65, 0
	s_branch .LBB0_280

; #define ATT_LOADKV(dst, nn) do { const bf16* src_ = qcol + (rowbase + (size_t)(128 * (nn) + srow) * dil) * NQKV + 1024 + sch * 8; const size_t st_ = (size_t)32 * dil * NQKV; \
;         _Pragma("unroll") for (int i_ = 0; i_ < 4; ++i_) { dst[i_] = __builtin_nontemporal_load((const v4u*)(src_ + i_ * st_)); dst[4 + i_] = __builtin_nontemporal_load((const v4u*)(src_ + i_ * st_ + 1024)); } } while (0)
; #define ATT_LOADQ(nn) do { const bf16* src_ = qcol + (rowbase + (size_t)(128 * (nn) + 16 * w + lq) * dil) * NQKV + 8 * gq; \
;         _Pragma("unroll") for (int s_ = 0; s_ < 4; ++s_) qn[s_] = __builtin_nontemporal_load((const bf16x8*)(src_ + 32 * s_)); } while (0)
; __device__ __forceinline__ void segment(LAS unsigned char* lds, const bf16* __restrict__ QKV, bf16* __restrict__ Og, float* __restrict__ L2, int bl, int g, int h, int r, int dil, int n0, int cnt, int tid) {
;     ...
;         if (n + 1 < n0 + cnt) { ATT_LOADKV(kv, n + 1); ATT_LOADQ(n + 1); }
;         const int cur = n & 1, prv = cur ^ 1;
;         f32x4 sc[9];
;         { bf16x8 kf[2][4];
.LBB0_298:
	s_cmp_eq_u32 s99, 0
	s_cbranch_scc1 .Lattstag_0
	s_sleep 10

; #define LAS __attribute__((address_space(3)))
; __device__ __forceinline__ unsigned swz(unsigned row) { return ((row & 3u) << 2) | ((row >> 2) & 3u); }
; __device__ __forceinline__ void segment(LAS unsigned char* lds, const bf16* __restrict__ QKV, bf16* __restrict__ Og, float* __restrict__ L2, int bl, int g, int h, int r, int dil, int n0, int cnt, int tid) {
;     const int lane = tid & 63, w = __builtin_amdgcn_readfirstlane(tid >> 6), lq = lane & 15, gq = lane >> 4;
;     const size_t rowbase = (size_t)bl * SEQ + r;
;     const bf16* qcol = QKV + (size_t)g * 3072 + h * 128;
;     const int srow = tid >> 4, sch = tid & 15;
;     const unsigned sdst = 256u * srow + 16u * ((unsigned)sch ^ swz(srow));
;     const unsigned sdstv = VBASE + 256u * srow + 16u * ((unsigned)sch ^ (2u * (srow & 7)));
;     unsigned koff[4], voff[8];
; #pragma unroll
;     for (int s = 0; s < 4; ++s) koff[s] = 256u * lq + 16u * ((unsigned)(4 * s + gq) ^ swz(lq));
;     { const unsigned q4 = lq >> 2, p4 = lq & 3, rowv = 4 * gq + q4;
; #pragma unroll
;       for (int c = 0; c < 8; ++c) voff[c] = 256u * rowv + 16u * ((unsigned)(2 * c + (p4 & 1)) ^ (2u * (rowv & 7))) + 8u * (p4 >> 1); }
;     const float cb = exp2f(-8.0f * (float)(g * 8 + h + 1) / 24.0f) * (float)dil * 1.4426950408889634f;
;     const float basel = -cb * (float)(128 + lq - 4 * gq);
;     v4u kv[8]; bf16x8 qn[4], qf[4];
; __device__ __forceinline__ void phase(LAS unsigned char* lds, const bf16* QKV, bf16* Og, float* L2, int tid) {
;     for (int it = blockIdx.x; it < 768; it += gridDim.x) {
.LBB0_430:
	s_cmp_lt_i32 s84, 5
	s_cselect_b64 s[2:3], -1, 0
	s_and_b64 s[0:1], s[2:3], s[0:1]
	s_andn2_b64 vcc, exec, s[0:1]
	s_cbranch_vccnz .LBB0_456
	v_readfirstlane_b32 s99, v154
	s_nop 3
	s_lshr_b32 s99, s99, 6
	s_cmp_ge_u32 s99, 4
	s_cselect_b32 s99, 1, 0
	v_writelane_b32 v239, s2, 63
	s_nop 0
	v_readlane_b32 s0, v239, 0
	s_cmpk_gt_i32 s0, 0x2ff
	v_writelane_b32 v238, s3, 0
	s_cbranch_scc1 .LBB0_455
	v_lshlrev_b32_e32 v5, 2, v154
	v_and_b32_e32 v119, 15, v154
	v_bfe_u32 v1, v154, 4, 2
	v_and_b32_e32 v6, 12, v5
	v_bfe_u32 v7, v154, 2, 2
	v_lshrrev_b32_e32 v2, 2, v154
	v_lshlrev_b32_e32 v4, 8, v119
	v_or_b32_e32 v8, v6, v7
	v_bitop3_b32 v6, v6, v1, v7 bitop3:0x36
	v_lshrrev_b32_e32 v122, 4, v154
	v_and_b32_e32 v2, 12, v2
	v_bfe_u32 v3, v154, 6, 2
	v_lshl_or_b32 v123, v6, 4, v4
	v_bitop3_b32 v6, v1, v8, 4 bitop3:0x36
	v_lshlrev_b32_e32 v0, 8, v122
	v_bitop3_b32 v2, v2, v119, v3 bitop3:0x36
	v_lshl_or_b32 v124, v6, 4, v4
	v_bitop3_b32 v6, v1, v8, 8 bitop3:0x36
	v_lshl_or_b32 v125, v6, 4, v4
	v_bitop3_b32 v6, v1, v8, 12 bitop3:0x36
	v_lshl_or_b32 v127, v2, 4, v0
	v_lshlrev_b32_e32 v2, 2, v1
	v_lshl_or_b32 v126, v6, 4, v4
	v_or_b32_e32 v4, v2, v7
	v_lshlrev_b32_e32 v7, 1, v4
	v_and_b32_e32 v6, 1, v154
	v_and_b32_e32 v8, 14, v7
	v_and_b32_e32 v5, 8, v5
	v_lshl_or_b32 v4, v4, 8, v5
	v_or_b32_e32 v5, v8, v6
	v_lshl_or_b32 v128, v5, 4, v4
	v_or_b32_e32 v5, 2, v6
	v_bitop3_b32 v5, v7, v5, 14 bitop3:0x6c
	v_lshl_or_b32 v129, v5, 4, v4
	v_or_b32_e32 v5, 4, v6
	v_bitop3_b32 v5, v7, v5, 14 bitop3:0x6c
	v_lshrrev_b32_e32 v3, 3, v154
	v_lshl_or_b32 v130, v5, 4, v4
	v_or_b32_e32 v5, 6, v6
	v_bitop3_b32 v3, v3, v119, 14 bitop3:0x6c
	v_bitop3_b32 v5, v7, v5, 14 bitop3:0x6c
	v_lshlrev_b32_e32 v3, 4, v3
	v_lshl_or_b32 v131, v5, 4, v4
	v_or_b32_e32 v5, 8, v6
	s_mov_b32 s0, 0x10000
	v_bitop3_b32 v5, v7, v5, 14 bitop3:0x6c
	v_or3_b32 v136, v3, v0, s0
	v_or_b32_e32 v0, 0x80, v119
	v_lshl_or_b32 v132, v5, 4, v4
	v_or_b32_e32 v5, 10, v6
	v_sub_u32_e32 v0, v0, v2
	v_bitop3_b32 v5, v7, v5, 14 bitop3:0x6c
	v_cvt_f32_ubyte0_e32 v137, v0
	v_or_b32_e32 v0, 1, v2
	v_lshl_or_b32 v133, v5, 4, v4
	v_or_b32_e32 v5, 12, v6
	v_cmp_ge_u32_e64 s[4:5], v2, v119
	v_cmp_ge_u32_e64 s[6:7], v0, v119
	v_or_b32_e32 v0, 2, v2
	v_or_b32_e32 v3, 3, v2
	v_cmp_gt_u32_e64 s[12:13], v2, v119
	v_cmp_lt_u32_e64 s[14:15], v2, v119
	v_mbcnt_lo_u32_b32 v2, -1, 0
	v_bitop3_b32 v5, v7, v5, 14 bitop3:0x6c
	v_mbcnt_hi_u32_b32 v2, -1, v2
	v_lshl_or_b32 v134, v5, 4, v4
	v_bitop3_b32 v5, v7, v6, 14 bitop3:0x4e
	v_and_b32_e32 v6, 64, v2
	v_lshl_or_b32 v135, v5, 4, v4
	v_xor_b32_e32 v5, 16, v2
	v_add_u32_e32 v6, 64, v6
	v_cmp_lt_i32_e32 vcc, v5, v6
	v_cmp_ge_u32_e64 s[10:11], v3, v119
	v_cmp_gt_u32_e64 s[18:19], v3, v119
	v_cndmask_b32_e32 v5, v2, v5, vcc
	v_lshlrev_b32_e32 v139, 2, v5
	v_xor_b32_e32 v5, 32, v2
	v_cmp_lt_i32_e32 vcc, v5, v6
	v_mov_b32_e32 v3, 0
	s_mov_b64 s[0:1], 0x7c00000
	v_cndmask_b32_e32 v2, v2, v5, vcc
	v_lshlrev_b32_e32 v140, 2, v2
	v_lshlrev_b32_e32 v2, 4, v1
	v_lshl_add_u64 v[6:7], s[82:83], 0, v[2:3]
	v_cmp_ge_u32_e64 s[8:9], v0, v119
	v_cmp_gt_u32_e64 s[16:17], v0, v119
	v_lshlrev_b32_e32 v0, 3, v119
	v_lshlrev_b32_e32 v4, 3, v1
	v_lshl_add_u64 v[68:69], s[80:81], 0, v[2:3]
	v_lshl_add_u64 v[70:71], v[6:7], 0, s[0:1]
	v_lshlrev_b32_e32 v2, 4, v119
	v_readlane_b32 s0, v239, 0
	v_or_b32_e32 v138, 0xffffff80, v122
	s_mov_b32 s41, 0
	v_cmp_eq_u32_e64 s[2:3], 0, v1
	v_lshl_add_u64 v[72:73], s[82:83], 0, v[2:3]
	v_mov_b32_e32 v141, 0x42800000
	v_lshlrev_b32_e32 v74, 1, v4
	v_mov_b32_e32 v75, v3
	v_lshlrev_b32_e32 v76, 1, v0
	v_mov_b32_e32 v77, v3
	v_mov_b64_e32 v[78:79], 0x2d0000
	v_mov_b64_e32 v[80:81], 0x240000
	v_mov_b64_e32 v[82:83], 0x360000
	v_mov_b64_e32 v[84:85], 0x3f0000
	v_mov_b32_e32 v142, 0xff800000
	s_mov_b32 s25, s0
	s_branch .LBB0_434
